# both GEMM K-loops: peeled final K-iteration for a workgroup's last unit that drops the 14 useless next-unit prefetch LDS-DMAs (waits re-derived 8,2,0,0); on top of stage B
# speedup vs baseline: 1.0114x; 1.0114x over previous
; template <class Epi, class Sched, bool ALIGN_EPI = false, bool SP2 = true>
; DI void gemm_phase(LAS unsigned char* lds, const Gemm g, const Sched& S, const Epi& E, f32x4 (&acc)[2][2][4][2]) {
;     ...
;         const bool has_next = S.next(ui + 1, nxt);
;         const char* nA = has_next ? (const char*)g.A + (size_t)nxt.pm * tstep : cA; const char* nB = has_next ? (const char*)g.Bt + (size_t)nxt.pn * tstep : cB;
;         for (int t = 0; t < nt; t += 2) {
;             const bool last = (t == nt - 2);
;             const char* a1 = cA + (size_t)(t + 1) * kstep;
;             const char* a2 = last ? nA : cA + (size_t)(t + 2) * kstep; const char* b2 = last ? nB : cB + (size_t)(t + 2) * kstep;
.LBB0_159:
	s_cmp_lg_u32 s62, 12
	s_cbranch_scc1 .Lg1_norm
	s_cmp_eq_u64 s[20:21], 0
	s_cbranch_scc1 .Lpeel_g1

; #define PG8_STAGE(bufoff, gbase, voff) do { _Pragma("unroll") for (int _i = 0; _i < 2; ++_i) \
;         __builtin_amdgcn_global_load_lds((const unsigned*)((const char*)(gbase) + (voff)[_i]), (LAS unsigned*)(lds + (bufoff) + ldsw + _i * 8192), 16, 0, 0); } while (0)
; #define PG8_LDA(dst, b, h) do { _Pragma("unroll") for (int m = 0; m < 4; ++m) _Pragma("unroll") for (int k = 0; k < 2; ++k) dst[m][k] = *(const LAS bf16x8*)(lds + PG8_SA(b, h) + aoff + m * 2048 + k * 1024); } while (0)
; #define PG8_LDB(dst, b, h) do { _Pragma("unroll") for (int n = 0; n < 2; ++n) _Pragma("unroll") for (int k = 0; k < 2; ++k) dst[n][k] = *(const LAS bf16x8*)(lds + PG8_SB(b, h) + boff + n * 2048 + k * 1024); } while (0)
; #define PG8_MMA(ai, bj, At, Bt) do { __builtin_amdgcn_s_setprio(1); _Pragma("unroll") for (int m = 0; m < 4; ++m) _Pragma("unroll") for (int n = 0; n < 2; ++n) _Pragma("unroll") for (int k = 0; k < 2; ++k) \
;         acc[ai][bj][m][n] = __builtin_amdgcn_mfma_f32_16x16x32_bf16(Bt[n][k], At[m][k], acc[ai][bj][m][n], 0, 0, 0); __builtin_amdgcn_s_setprio(0); } while (0)
; #define PG8_WAIT_V(n) asm volatile("s_waitcnt vmcnt(" #n ")" ::: "memory")
; #define PG8_WAIT_L(n) asm volatile("s_waitcnt lgkmcnt(" #n ")" ::: "memory")
; #define PG8_BAR __builtin_amdgcn_s_barrier()
; #define PG8_SCHED __builtin_amdgcn_sched_barrier(0)
; template <class Epi, class Sched, bool ALIGN_EPI = false, bool SP2 = true>
; DI void gemm_phase(LAS unsigned char* lds, const Gemm g, const Sched& S, const Epi& E, f32x4 (&acc)[2][2][4][2]) {
;     ...
;             PG8_LDB(B0, 0, 0); PG8_LDB(B1, 0, 1); PG8_SCHED; PG8_LDA(At, 0, 0); PG8_STAGE(PG8_SA(1, 1), a1 + hstep, voffA);
;             PG8_WAIT_V(8); PG8_WAIT_L(0); PG8_BAR; PG8_MMA(0, 0, At, B0); PG8_MMA(0, 1, At, B1); PG8_BAR; PG8_SCHED;
;             PG8_LDA(At, 0, 1); PG8_STAGE(PG8_SB(0, 0), b2, voffB); PG8_STAGE(PG8_SB(0, 1), b2 + hstep, voffB); PG8_STAGE(PG8_SA(0, 0), a2, voffA);
;             PG8_WAIT_V(8); PG8_WAIT_L(0); PG8_BAR; PG8_MMA(1, 0, At, B0); PG8_MMA(1, 1, At, B1); PG8_BAR; PG8_SCHED;
.Lpeel_g1:
	ds_read_b128 v[150:153], v164
	ds_read_b128 v[154:157], v164 offset:1024
	ds_read_b128 v[158:161], v164 offset:2048
	ds_read_b128 v[168:171], v164 offset:3072
	ds_read_b128 v[172:175], v165
	ds_read_b128 v[180:183], v165 offset:1024
	ds_read_b128 v[184:187], v165 offset:2048
	ds_read_b128 v[188:191], v165 offset:3072
	s_add_u32 s30, s0, 0xfffc0080
	s_addc_u32 s31, s1, -1
	s_cmp_eq_u32 s62, 12
	s_cselect_b32 s35, s25, s31
	s_cselect_b32 s34, s52, s30
	s_cselect_b32 s31, s23, s55
	s_cselect_b32 s30, s53, s54
	v_lshl_add_u64 v[176:177], s[0:1], 0, v[146:147]
	s_add_i32 m0, s74, 0xc000
	ds_read_b128 v[192:195], v166
	ds_read_b128 v[196:199], v166 offset:1024
	ds_read_b128 v[202:205], v166 offset:2048
	ds_read_b128 v[206:209], v166 offset:3072
	ds_read_b128 v[210:213], v166 offset:4096
	ds_read_b128 v[214:217], v166 offset:5120
	ds_read_b128 v[218:221], v166 offset:6144
	ds_read_b128 v[222:225], v166 offset:7168
	global_load_lds_dwordx4 v[176:177], off
	v_lshl_add_u64 v[176:177], s[0:1], 0, v[148:149]
	s_add_i32 m0, s74, 0xe000
	s_nop 0
	global_load_lds_dwordx4 v[176:177], off
	s_waitcnt vmcnt(8)
	s_waitcnt lgkmcnt(0)
	s_barrier
	s_setprio 1
	s_waitcnt lgkmcnt(0)
	v_mfma_f32_16x16x32_bf16 v[124:127], v[150:153], v[192:195], v[124:127]
	v_mfma_f32_16x16x32_bf16 v[120:123], v[158:161], v[192:195], v[120:123]
	v_mfma_f32_16x16x32_bf16 v[108:111], v[150:153], v[202:205], v[108:111]
	v_mfma_f32_16x16x32_bf16 v[104:107], v[158:161], v[202:205], v[104:107]
	v_mfma_f32_16x16x32_bf16 v[92:95], v[150:153], v[210:213], v[92:95]
	v_mfma_f32_16x16x32_bf16 v[88:91], v[158:161], v[210:213], v[88:91]
	v_mfma_f32_16x16x32_bf16 v[76:79], v[150:153], v[218:221], v[76:79]
	v_mfma_f32_16x16x32_bf16 v[72:75], v[158:161], v[218:221], v[72:75]
	v_mfma_f32_16x16x32_bf16 v[124:127], v[154:157], v[196:199], v[124:127]
	v_mfma_f32_16x16x32_bf16 v[120:123], v[168:171], v[196:199], v[120:123]
	v_mfma_f32_16x16x32_bf16 v[108:111], v[154:157], v[206:209], v[108:111]
	v_mfma_f32_16x16x32_bf16 v[104:107], v[168:171], v[206:209], v[104:107]
	v_mfma_f32_16x16x32_bf16 v[92:95], v[154:157], v[214:217], v[92:95]
	v_mfma_f32_16x16x32_bf16 v[88:91], v[168:171], v[214:217], v[88:91]
	v_mfma_f32_16x16x32_bf16 v[76:79], v[154:157], v[222:225], v[76:79]
	v_mfma_f32_16x16x32_bf16 v[72:75], v[168:171], v[222:225], v[72:75]
	s_setprio 0
	s_setprio 1
	v_mfma_f32_16x16x32_bf16 v[116:119], v[172:175], v[192:195], v[116:119]
	v_mfma_f32_16x16x32_bf16 v[112:115], v[184:187], v[192:195], v[112:115]
	v_mfma_f32_16x16x32_bf16 v[100:103], v[172:175], v[202:205], v[100:103]
	v_mfma_f32_16x16x32_bf16 v[96:99], v[184:187], v[202:205], v[96:99]
	v_mfma_f32_16x16x32_bf16 v[84:87], v[172:175], v[210:213], v[84:87]
	v_mfma_f32_16x16x32_bf16 v[80:83], v[184:187], v[210:213], v[80:83]
	v_mfma_f32_16x16x32_bf16 v[68:71], v[172:175], v[218:221], v[68:71]
	v_mfma_f32_16x16x32_bf16 v[64:67], v[184:187], v[218:221], v[64:67]
	v_mfma_f32_16x16x32_bf16 v[116:119], v[180:183], v[196:199], v[116:119]
	v_mfma_f32_16x16x32_bf16 v[112:115], v[188:191], v[196:199], v[112:115]
	v_mfma_f32_16x16x32_bf16 v[100:103], v[180:183], v[206:209], v[100:103]
	v_mfma_f32_16x16x32_bf16 v[96:99], v[188:191], v[206:209], v[96:99]
	v_mfma_f32_16x16x32_bf16 v[84:87], v[180:183], v[214:217], v[84:87]
	v_mfma_f32_16x16x32_bf16 v[80:83], v[188:191], v[214:217], v[80:83]
	v_mfma_f32_16x16x32_bf16 v[68:71], v[180:183], v[222:225], v[68:71]
	v_mfma_f32_16x16x32_bf16 v[64:67], v[188:191], v[222:225], v[64:67]
	s_setprio 0
	s_barrier
	s_add_i32 s63, s82, s39
	v_lshl_add_u64 v[176:177], s[30:31], 0, v[130:131]
	s_mov_b32 m0, s63
	ds_read_b128 v[192:195], v166 offset:16384
	ds_read_b128 v[196:199], v166 offset:17408
	ds_read_b128 v[202:205], v166 offset:18432
	ds_read_b128 v[206:209], v166 offset:19456
	ds_read_b128 v[210:213], v166 offset:20480
	ds_read_b128 v[214:217], v166 offset:21504
	ds_read_b128 v[218:221], v166 offset:22528
	ds_read_b128 v[222:225], v166 offset:23552
	s_add_i32 m0, s63, 0x2000
	s_add_u32 s72, s30, 0x10000
	v_lshl_add_u64 v[226:227], s[30:31], 0, v[134:135]
	s_addc_u32 s73, s31, 0
	s_add_i32 s63, s83, s39
	v_lshl_add_u64 v[228:229], s[72:73], 0, v[130:131]
	s_mov_b32 m0, s63
	v_lshl_add_u64 v[230:231], s[34:35], 0, v[132:133]
	v_lshl_add_u64 v[228:229], s[72:73], 0, v[134:135]
	s_add_i32 m0, s63, 0x2000
	s_nop 0
	v_lshl_add_u64 v[228:229], s[34:35], 0, v[128:129]
	s_mov_b32 m0, s74
	s_nop 0
	s_mov_b32 m0, s75
	s_nop 0
	s_waitcnt vmcnt(2)
	s_waitcnt lgkmcnt(0)
	s_barrier
	s_setprio 1
	s_waitcnt lgkmcnt(0)
	v_mfma_f32_16x16x32_bf16 v[60:63], v[150:153], v[192:195], v[60:63]
	v_mfma_f32_16x16x32_bf16 v[56:59], v[158:161], v[192:195], v[56:59]
	v_mfma_f32_16x16x32_bf16 v[44:47], v[150:153], v[202:205], v[44:47]
	v_mfma_f32_16x16x32_bf16 v[40:43], v[158:161], v[202:205], v[40:43]
	v_mfma_f32_16x16x32_bf16 v[28:31], v[150:153], v[210:213], v[28:31]
	v_mfma_f32_16x16x32_bf16 v[24:27], v[158:161], v[210:213], v[24:27]
	v_mfma_f32_16x16x32_bf16 v[12:15], v[150:153], v[218:221], v[12:15]
	v_mfma_f32_16x16x32_bf16 v[8:11], v[158:161], v[218:221], v[8:11]
	v_mfma_f32_16x16x32_bf16 v[60:63], v[154:157], v[196:199], v[60:63]
	v_mfma_f32_16x16x32_bf16 v[56:59], v[168:171], v[196:199], v[56:59]
	v_mfma_f32_16x16x32_bf16 v[44:47], v[154:157], v[206:209], v[44:47]
	v_mfma_f32_16x16x32_bf16 v[40:43], v[168:171], v[206:209], v[40:43]
	v_mfma_f32_16x16x32_bf16 v[28:31], v[154:157], v[214:217], v[28:31]
	v_mfma_f32_16x16x32_bf16 v[24:27], v[168:171], v[214:217], v[24:27]
	v_mfma_f32_16x16x32_bf16 v[12:15], v[154:157], v[222:225], v[12:15]
	v_mfma_f32_16x16x32_bf16 v[8:11], v[168:171], v[222:225], v[8:11]
	s_setprio 0
	s_setprio 1
	v_mfma_f32_16x16x32_bf16 v[52:55], v[172:175], v[192:195], v[52:55]
	v_mfma_f32_16x16x32_bf16 v[48:51], v[184:187], v[192:195], v[48:51]
	v_mfma_f32_16x16x32_bf16 v[36:39], v[172:175], v[202:205], v[36:39]
	v_mfma_f32_16x16x32_bf16 v[32:35], v[184:187], v[202:205], v[32:35]
	v_mfma_f32_16x16x32_bf16 v[20:23], v[172:175], v[210:213], v[20:23]
	v_mfma_f32_16x16x32_bf16 v[16:19], v[184:187], v[210:213], v[16:19]
	v_mfma_f32_16x16x32_bf16 v[4:7], v[172:175], v[218:221], v[4:7]
	v_mfma_f32_16x16x32_bf16 v[0:3], v[184:187], v[218:221], v[0:3]
	v_mfma_f32_16x16x32_bf16 v[52:55], v[180:183], v[196:199], v[52:55]
	v_mfma_f32_16x16x32_bf16 v[48:51], v[188:191], v[196:199], v[48:51]
	v_mfma_f32_16x16x32_bf16 v[36:39], v[180:183], v[206:209], v[36:39]
	v_mfma_f32_16x16x32_bf16 v[32:35], v[188:191], v[206:209], v[32:35]
	v_mfma_f32_16x16x32_bf16 v[20:23], v[180:183], v[214:217], v[20:23]
	v_mfma_f32_16x16x32_bf16 v[16:19], v[188:191], v[214:217], v[16:19]
	v_mfma_f32_16x16x32_bf16 v[4:7], v[180:183], v[222:225], v[4:7]
	v_mfma_f32_16x16x32_bf16 v[0:3], v[188:191], v[222:225], v[0:3]
	s_setprio 0
	s_barrier
; #define PG8_STAGE(bufoff, gbase, voff) do { _Pragma("unroll") for (int _i = 0; _i < 2; ++_i) \
;         __builtin_amdgcn_global_load_lds((const unsigned*)((const char*)(gbase) + (voff)[_i]), (LAS unsigned*)(lds + (bufoff) + ldsw + _i * 8192), 16, 0, 0); } while (0)
; #define PG8_LDA(dst, b, h) do { _Pragma("unroll") for (int m = 0; m < 4; ++m) _Pragma("unroll") for (int k = 0; k < 2; ++k) dst[m][k] = *(const LAS bf16x8*)(lds + PG8_SA(b, h) + aoff + m * 2048 + k * 1024); } while (0)
; #define PG8_LDB(dst, b, h) do { _Pragma("unroll") for (int n = 0; n < 2; ++n) _Pragma("unroll") for (int k = 0; k < 2; ++k) dst[n][k] = *(const LAS bf16x8*)(lds + PG8_SB(b, h) + boff + n * 2048 + k * 1024); } while (0)
; #define PG8_MMA(ai, bj, At, Bt) do { __builtin_amdgcn_s_setprio(1); _Pragma("unroll") for (int m = 0; m < 4; ++m) _Pragma("unroll") for (int n = 0; n < 2; ++n) _Pragma("unroll") for (int k = 0; k < 2; ++k) \
;         acc[ai][bj][m][n] = __builtin_amdgcn_mfma_f32_16x16x32_bf16(Bt[n][k], At[m][k], acc[ai][bj][m][n], 0, 0, 0); __builtin_amdgcn_s_setprio(0); } while (0)
; #define PG8_WAIT_V(n) asm volatile("s_waitcnt vmcnt(" #n ")" ::: "memory")
; #define PG8_WAIT_L(n) asm volatile("s_waitcnt lgkmcnt(" #n ")" ::: "memory")
; #define PG8_BAR __builtin_amdgcn_s_barrier()
; #define PG8_SCHED __builtin_amdgcn_sched_barrier(0)
; template <class Epi, class Sched, bool ALIGN_EPI = false, bool SP2 = true>
; DI void gemm_phase(LAS unsigned char* lds, const Gemm g, const Sched& S, const Epi& E, f32x4 (&acc)[2][2][4][2]) {
;     ...
;             PG8_LDB(B0, 1, 0); PG8_LDB(B1, 1, 1); PG8_SCHED; PG8_LDA(At, 1, 0); PG8_STAGE(PG8_SA(0, 1), a2 + hstep, voffA);
;             PG8_WAIT_V(8); PG8_WAIT_L(0); PG8_BAR; PG8_MMA(0, 0, At, B0); PG8_MMA(0, 1, At, B1); PG8_BAR; PG8_SCHED;
;             PG8_LDA(At, 1, 1); PG8_STAGE(PG8_SB(1, 0), b3, voffB); PG8_STAGE(PG8_SB(1, 1), b3 + hstep, voffB); PG8_STAGE(PG8_SA(1, 0), a3, voffA);
;             PG8_WAIT_V(8); PG8_WAIT_L(0); PG8_BAR; PG8_MMA(1, 0, At, B0); PG8_MMA(1, 1, At, B1); PG8_BAR; PG8_SCHED;
	s_add_i32 s63, 0, 0x18000
	s_add_i32 s64, 0, 0x1c000
	v_add_u32_e32 v168, s63, v143
	v_add_u32_e32 v178, s64, v143
	ds_read_b128 v[150:153], v168
	ds_read_b128 v[154:157], v168 offset:1024
	ds_read_b128 v[158:161], v168 offset:2048
	ds_read_b128 v[168:171], v168 offset:3072
	ds_read_b128 v[172:175], v178
	ds_read_b128 v[180:183], v178 offset:1024
	ds_read_b128 v[184:187], v178 offset:2048
	ds_read_b128 v[188:191], v178 offset:3072
	s_add_u32 s34, s34, 0x40000
	s_addc_u32 s35, s35, 0
	s_mov_b32 m0, s76
	v_lshl_add_u64 v[232:233], s[34:35], 0, v[128:129]
	ds_read_b128 v[192:195], v166 offset:32768
	ds_read_b128 v[196:199], v166 offset:33792
	ds_read_b128 v[202:205], v166 offset:34816
	ds_read_b128 v[206:209], v166 offset:35840
	ds_read_b128 v[210:213], v166 offset:36864
	ds_read_b128 v[214:217], v166 offset:37888
	ds_read_b128 v[218:221], v166 offset:38912
	ds_read_b128 v[222:225], v166 offset:39936
	v_lshl_add_u64 v[232:233], s[34:35], 0, v[132:133]
	s_mov_b32 m0, s77
	s_nop 0
	s_waitcnt vmcnt(0)
	s_waitcnt lgkmcnt(0)
	s_barrier
	s_setprio 1
	s_waitcnt lgkmcnt(0)
	v_mfma_f32_16x16x32_bf16 v[124:127], v[150:153], v[192:195], v[124:127]
	v_mfma_f32_16x16x32_bf16 v[120:123], v[158:161], v[192:195], v[120:123]
	v_mfma_f32_16x16x32_bf16 v[108:111], v[150:153], v[202:205], v[108:111]
	v_mfma_f32_16x16x32_bf16 v[104:107], v[158:161], v[202:205], v[104:107]
	v_mfma_f32_16x16x32_bf16 v[92:95], v[150:153], v[210:213], v[92:95]
	v_mfma_f32_16x16x32_bf16 v[88:91], v[158:161], v[210:213], v[88:91]
	v_mfma_f32_16x16x32_bf16 v[76:79], v[150:153], v[218:221], v[76:79]
	v_mfma_f32_16x16x32_bf16 v[72:75], v[158:161], v[218:221], v[72:75]
	v_mfma_f32_16x16x32_bf16 v[124:127], v[154:157], v[196:199], v[124:127]
	v_mfma_f32_16x16x32_bf16 v[120:123], v[168:171], v[196:199], v[120:123]
	v_mfma_f32_16x16x32_bf16 v[108:111], v[154:157], v[206:209], v[108:111]
	v_mfma_f32_16x16x32_bf16 v[104:107], v[168:171], v[206:209], v[104:107]
	v_mfma_f32_16x16x32_bf16 v[92:95], v[154:157], v[214:217], v[92:95]
	v_mfma_f32_16x16x32_bf16 v[88:91], v[168:171], v[214:217], v[88:91]
	v_mfma_f32_16x16x32_bf16 v[76:79], v[154:157], v[222:225], v[76:79]
	v_mfma_f32_16x16x32_bf16 v[72:75], v[168:171], v[222:225], v[72:75]
	s_setprio 0
	s_setprio 1
	v_mfma_f32_16x16x32_bf16 v[116:119], v[172:175], v[192:195], v[116:119]
	v_mfma_f32_16x16x32_bf16 v[112:115], v[184:187], v[192:195], v[112:115]
	v_mfma_f32_16x16x32_bf16 v[100:103], v[172:175], v[202:205], v[100:103]
	v_mfma_f32_16x16x32_bf16 v[96:99], v[184:187], v[202:205], v[96:99]
	v_mfma_f32_16x16x32_bf16 v[84:87], v[172:175], v[210:213], v[84:87]
	v_mfma_f32_16x16x32_bf16 v[80:83], v[184:187], v[210:213], v[80:83]
	v_mfma_f32_16x16x32_bf16 v[68:71], v[172:175], v[218:221], v[68:71]
	v_mfma_f32_16x16x32_bf16 v[64:67], v[184:187], v[218:221], v[64:67]
	v_mfma_f32_16x16x32_bf16 v[116:119], v[180:183], v[196:199], v[116:119]
	v_mfma_f32_16x16x32_bf16 v[112:115], v[188:191], v[196:199], v[112:115]
	v_mfma_f32_16x16x32_bf16 v[100:103], v[180:183], v[206:209], v[100:103]
	v_mfma_f32_16x16x32_bf16 v[96:99], v[188:191], v[206:209], v[96:99]
	v_mfma_f32_16x16x32_bf16 v[84:87], v[180:183], v[214:217], v[84:87]
	v_mfma_f32_16x16x32_bf16 v[80:83], v[188:191], v[214:217], v[80:83]
	v_mfma_f32_16x16x32_bf16 v[68:71], v[180:183], v[222:225], v[68:71]
	v_mfma_f32_16x16x32_bf16 v[64:67], v[188:191], v[222:225], v[64:67]
	s_setprio 0
	s_barrier
	s_add_i32 s34, s63, s39
	v_lshl_add_u64 v[176:177], v[176:177], 0, s[14:15]
	s_mov_b32 m0, s34
	ds_read_b128 v[192:195], v166 offset:49152
	ds_read_b128 v[196:199], v166 offset:50176
	ds_read_b128 v[202:205], v166 offset:51200
	ds_read_b128 v[206:209], v166 offset:52224
	ds_read_b128 v[210:213], v166 offset:53248
	ds_read_b128 v[214:217], v166 offset:54272
	ds_read_b128 v[218:221], v166 offset:55296
	ds_read_b128 v[222:225], v166 offset:56320
	s_add_i32 m0, s34, 0x2000
	s_add_u32 s30, s30, 0x10080
	v_lshl_add_u64 v[176:177], v[226:227], 0, s[14:15]
	s_addc_u32 s31, s31, 0
	s_add_i32 s34, s64, s39
	v_lshl_add_u64 v[176:177], s[30:31], 0, v[130:131]
	s_mov_b32 m0, s34
	s_nop 0
	v_lshl_add_u64 v[176:177], s[30:31], 0, v[134:135]
	s_add_i32 m0, s34, 0x2000
	s_nop 0
	v_lshl_add_u64 v[176:177], v[228:229], 0, s[14:15]
	s_mov_b32 m0, s80
	s_nop 0
	v_lshl_add_u64 v[176:177], v[230:231], 0, s[14:15]
	s_mov_b32 m0, s81
	s_nop 0
	s_waitcnt vmcnt(0)
	s_waitcnt lgkmcnt(0)
	s_barrier
	s_setprio 1
	s_waitcnt lgkmcnt(0)
	v_mfma_f32_16x16x32_bf16 v[60:63], v[150:153], v[192:195], v[60:63]
	v_mfma_f32_16x16x32_bf16 v[56:59], v[158:161], v[192:195], v[56:59]
	v_mfma_f32_16x16x32_bf16 v[44:47], v[150:153], v[202:205], v[44:47]
	v_mfma_f32_16x16x32_bf16 v[40:43], v[158:161], v[202:205], v[40:43]
	v_mfma_f32_16x16x32_bf16 v[28:31], v[150:153], v[210:213], v[28:31]
	v_mfma_f32_16x16x32_bf16 v[24:27], v[158:161], v[210:213], v[24:27]
	v_mfma_f32_16x16x32_bf16 v[12:15], v[150:153], v[218:221], v[12:15]
	v_mfma_f32_16x16x32_bf16 v[8:11], v[158:161], v[218:221], v[8:11]
	v_mfma_f32_16x16x32_bf16 v[60:63], v[154:157], v[196:199], v[60:63]
	v_mfma_f32_16x16x32_bf16 v[56:59], v[168:171], v[196:199], v[56:59]
	v_mfma_f32_16x16x32_bf16 v[44:47], v[154:157], v[206:209], v[44:47]
	v_mfma_f32_16x16x32_bf16 v[40:43], v[168:171], v[206:209], v[40:43]
	v_mfma_f32_16x16x32_bf16 v[28:31], v[154:157], v[214:217], v[28:31]
	v_mfma_f32_16x16x32_bf16 v[24:27], v[168:171], v[214:217], v[24:27]
	v_mfma_f32_16x16x32_bf16 v[12:15], v[154:157], v[222:225], v[12:15]
	v_mfma_f32_16x16x32_bf16 v[8:11], v[168:171], v[222:225], v[8:11]
	s_setprio 0
	s_setprio 1
	v_mfma_f32_16x16x32_bf16 v[52:55], v[172:175], v[192:195], v[52:55]
	v_mfma_f32_16x16x32_bf16 v[48:51], v[184:187], v[192:195], v[48:51]
	v_mfma_f32_16x16x32_bf16 v[36:39], v[172:175], v[202:205], v[36:39]
	v_mfma_f32_16x16x32_bf16 v[32:35], v[184:187], v[202:205], v[32:35]
	v_mfma_f32_16x16x32_bf16 v[20:23], v[172:175], v[210:213], v[20:23]
	v_mfma_f32_16x16x32_bf16 v[16:19], v[184:187], v[210:213], v[16:19]
	v_mfma_f32_16x16x32_bf16 v[4:7], v[172:175], v[218:221], v[4:7]
	v_mfma_f32_16x16x32_bf16 v[0:3], v[184:187], v[218:221], v[0:3]
	v_mfma_f32_16x16x32_bf16 v[52:55], v[180:183], v[196:199], v[52:55]
	v_mfma_f32_16x16x32_bf16 v[48:51], v[188:191], v[196:199], v[48:51]
	v_mfma_f32_16x16x32_bf16 v[36:39], v[180:183], v[206:209], v[36:39]
	v_mfma_f32_16x16x32_bf16 v[32:35], v[188:191], v[206:209], v[32:35]
	v_mfma_f32_16x16x32_bf16 v[20:23], v[180:183], v[214:217], v[20:23]
	v_mfma_f32_16x16x32_bf16 v[16:19], v[188:191], v[214:217], v[16:19]
	v_mfma_f32_16x16x32_bf16 v[4:7], v[180:183], v[222:225], v[4:7]
	v_mfma_f32_16x16x32_bf16 v[0:3], v[188:191], v[222:225], v[0:3]
	s_setprio 0
	s_barrier
	s_add_i32 s62, s62, 2
	s_add_u32 s0, s0, 0x100
	s_addc_u32 s1, s1, 0
	s_add_u32 s54, s54, 0x100
	s_addc_u32 s55, s55, 0
	s_cmp_gt_u32 s62, 13
	s_branch .Lafter_g1
; #define PG8_STAGE(bufoff, gbase, voff) do { _Pragma("unroll") for (int _i = 0; _i < 2; ++_i) \
;         __builtin_amdgcn_global_load_lds((const unsigned*)((const char*)(gbase) + (voff)[_i]), (LAS unsigned*)(lds + (bufoff) + ldsw + _i * 8192), 16, 0, 0); } while (0)
; #define PG8_LDA(dst, b, h) do { _Pragma("unroll") for (int m = 0; m < 4; ++m) _Pragma("unroll") for (int k = 0; k < 2; ++k) dst[m][k] = *(const LAS bf16x8*)(lds + PG8_SA(b, h) + aoff + m * 2048 + k * 1024); } while (0)
; #define PG8_LDB(dst, b, h) do { _Pragma("unroll") for (int n = 0; n < 2; ++n) _Pragma("unroll") for (int k = 0; k < 2; ++k) dst[n][k] = *(const LAS bf16x8*)(lds + PG8_SB(b, h) + boff + n * 2048 + k * 1024); } while (0)
; #define PG8_MMA(ai, bj, At, Bt) do { __builtin_amdgcn_s_setprio(1); _Pragma("unroll") for (int m = 0; m < 4; ++m) _Pragma("unroll") for (int n = 0; n < 2; ++n) _Pragma("unroll") for (int k = 0; k < 2; ++k) \
;         acc[ai][bj][m][n] = __builtin_amdgcn_mfma_f32_16x16x32_bf16(Bt[n][k], At[m][k], acc[ai][bj][m][n], 0, 0, 0); __builtin_amdgcn_s_setprio(0); } while (0)
; #define PG8_WAIT_V(n) asm volatile("s_waitcnt vmcnt(" #n ")" ::: "memory")
; #define PG8_WAIT_L(n) asm volatile("s_waitcnt lgkmcnt(" #n ")" ::: "memory")
; #define PG8_BAR __builtin_amdgcn_s_barrier()
; #define PG8_SCHED __builtin_amdgcn_sched_barrier(0)
; template <class Epi, class Sched, bool ALIGN_EPI = false, bool SP2 = true>
; DI void gemm_phase(LAS unsigned char* lds, const Gemm g, const Sched& S, const Epi& E, f32x4 (&acc)[2][2][4][2]) {
;     ...
;             PG8_LDB(B0, 0, 0); PG8_LDB(B1, 0, 1); PG8_SCHED; PG8_LDA(At, 0, 0); PG8_STAGE(PG8_SA(1, 1), a1 + hstep, voffA);
;             PG8_WAIT_V(8); PG8_WAIT_L(0); PG8_BAR; PG8_MMA(0, 0, At, B0); PG8_MMA(0, 1, At, B1); PG8_BAR; PG8_SCHED;
;             PG8_LDA(At, 0, 1); PG8_STAGE(PG8_SB(0, 0), b2, voffB); PG8_STAGE(PG8_SB(0, 1), b2 + hstep, voffB); PG8_STAGE(PG8_SA(0, 0), a2, voffA);
;             PG8_WAIT_V(8); PG8_WAIT_L(0); PG8_BAR; PG8_MMA(1, 0, At, B0); PG8_MMA(1, 1, At, B1); PG8_BAR; PG8_SCHED;
.Lpeel_g2:
	v_add_u32_e32 v156, s35, v142
	v_add_u32_e32 v172, s36, v142
	s_add_u32 s18, s0, s16
	ds_read_b128 v[144:147], v156
	ds_read_b128 v[148:151], v156 offset:1024
	ds_read_b128 v[152:155], v156 offset:2048
	ds_read_b128 v[156:159], v156 offset:3072
	ds_read_b128 v[160:163], v172
	ds_read_b128 v[164:167], v172 offset:1024
	ds_read_b128 v[168:171], v172 offset:2048
	ds_read_b128 v[172:175], v172 offset:3072
	s_addc_u32 s19, s1, s17
	s_add_u32 s18, s18, 0x100
	s_addc_u32 s19, s19, 0
	s_add_u32 s60, s52, s16
	s_addc_u32 s61, s53, s17
	s_cmpk_eq_i32 s16, 0x700
	s_cselect_b32 s21, s55, s19
	s_cselect_b32 s20, s56, s18
	s_cselect_b32 s19, s57, s61
	s_cselect_b32 s18, s58, s60
	s_mov_b32 m0, s37
	v_lshl_add_u64 v[176:177], v[136:137], 0, s[16:17]
	ds_read_b128 v[180:183], v143
	ds_read_b128 v[184:187], v143 offset:1024
	ds_read_b128 v[188:191], v143 offset:2048
	ds_read_b128 v[192:195], v143 offset:3072
	ds_read_b128 v[196:199], v143 offset:4096
	ds_read_b128 v[202:205], v143 offset:5120
	ds_read_b128 v[206:209], v143 offset:6144
	ds_read_b128 v[210:213], v143 offset:7168
	global_load_lds_dwordx4 v[176:177], off
	v_lshl_add_u64 v[176:177], v[138:139], 0, s[16:17]
	s_mov_b32 m0, s38
	s_nop 0
	global_load_lds_dwordx4 v[176:177], off
	s_waitcnt vmcnt(8)
	s_waitcnt lgkmcnt(0)
	s_barrier
	s_setprio 1
	s_waitcnt lgkmcnt(0)
	v_mfma_f32_16x16x32_bf16 v[124:127], v[144:147], v[180:183], v[124:127]
	v_mfma_f32_16x16x32_bf16 v[112:115], v[152:155], v[180:183], v[112:115]
	v_mfma_f32_16x16x32_bf16 v[104:107], v[144:147], v[188:191], v[104:107]
	v_mfma_f32_16x16x32_bf16 v[96:99], v[152:155], v[188:191], v[96:99]
	v_mfma_f32_16x16x32_bf16 v[100:103], v[144:147], v[196:199], v[100:103]
	v_mfma_f32_16x16x32_bf16 v[88:91], v[152:155], v[196:199], v[88:91]
	v_mfma_f32_16x16x32_bf16 v[92:95], v[144:147], v[206:209], v[92:95]
	v_mfma_f32_16x16x32_bf16 v[84:87], v[152:155], v[206:209], v[84:87]
	v_mfma_f32_16x16x32_bf16 v[124:127], v[148:151], v[184:187], v[124:127]
	v_mfma_f32_16x16x32_bf16 v[112:115], v[156:159], v[184:187], v[112:115]
	v_mfma_f32_16x16x32_bf16 v[104:107], v[148:151], v[192:195], v[104:107]
	v_mfma_f32_16x16x32_bf16 v[96:99], v[156:159], v[192:195], v[96:99]
	v_mfma_f32_16x16x32_bf16 v[100:103], v[148:151], v[202:205], v[100:103]
	v_mfma_f32_16x16x32_bf16 v[88:91], v[156:159], v[202:205], v[88:91]
	v_mfma_f32_16x16x32_bf16 v[92:95], v[148:151], v[210:213], v[92:95]
	v_mfma_f32_16x16x32_bf16 v[84:87], v[156:159], v[210:213], v[84:87]
	s_setprio 0
	s_setprio 1
	v_mfma_f32_16x16x32_bf16 v[80:83], v[160:163], v[180:183], v[80:83]
	v_mfma_f32_16x16x32_bf16 v[60:63], v[168:171], v[180:183], v[60:63]
	v_mfma_f32_16x16x32_bf16 v[56:59], v[160:163], v[188:191], v[56:59]
	v_mfma_f32_16x16x32_bf16 v[48:51], v[168:171], v[188:191], v[48:51]
	v_mfma_f32_16x16x32_bf16 v[52:55], v[160:163], v[196:199], v[52:55]
	v_mfma_f32_16x16x32_bf16 v[40:43], v[168:171], v[196:199], v[40:43]
	v_mfma_f32_16x16x32_bf16 v[44:47], v[160:163], v[206:209], v[44:47]
	v_mfma_f32_16x16x32_bf16 v[20:23], v[168:171], v[206:209], v[20:23]
	v_mfma_f32_16x16x32_bf16 v[80:83], v[164:167], v[184:187], v[80:83]
	v_mfma_f32_16x16x32_bf16 v[60:63], v[172:175], v[184:187], v[60:63]
	v_mfma_f32_16x16x32_bf16 v[56:59], v[164:167], v[192:195], v[56:59]
	v_mfma_f32_16x16x32_bf16 v[48:51], v[172:175], v[192:195], v[48:51]
	v_mfma_f32_16x16x32_bf16 v[52:55], v[164:167], v[202:205], v[52:55]
	v_mfma_f32_16x16x32_bf16 v[40:43], v[172:175], v[202:205], v[40:43]
	v_mfma_f32_16x16x32_bf16 v[44:47], v[164:167], v[210:213], v[44:47]
	v_mfma_f32_16x16x32_bf16 v[20:23], v[172:175], v[210:213], v[20:23]
	s_setprio 0
	s_barrier
	s_mov_b32 m0, s39
	v_lshl_add_u64 v[176:177], s[18:19], 0, v[130:131]
	s_add_u32 s60, s18, 0x40000
	ds_read_b128 v[180:183], v143 offset:16384
	ds_read_b128 v[184:187], v143 offset:17408
	ds_read_b128 v[188:191], v143 offset:18432
	ds_read_b128 v[192:195], v143 offset:19456
	ds_read_b128 v[196:199], v143 offset:20480
	ds_read_b128 v[202:205], v143 offset:21504
	ds_read_b128 v[206:209], v143 offset:22528
	ds_read_b128 v[210:213], v143 offset:23552
	v_lshl_add_u64 v[214:215], s[18:19], 0, v[128:129]
	s_mov_b32 m0, s40
	s_addc_u32 s61, s19, 0
	v_lshl_add_u64 v[216:217], s[60:61], 0, v[130:131]
	s_mov_b32 m0, s41
	v_lshl_add_u64 v[218:219], s[20:21], 0, v[128:129]
	v_lshl_add_u64 v[216:217], s[60:61], 0, v[128:129]
	s_mov_b32 m0, s42
	s_nop 0
	v_lshl_add_u64 v[216:217], s[20:21], 0, v[130:131]
	s_mov_b32 m0, s5
	s_nop 0
	s_mov_b32 m0, s27
	s_nop 0
	s_waitcnt vmcnt(2)
	s_waitcnt lgkmcnt(0)
	s_barrier
; #define PG8_STAGE(bufoff, gbase, voff) do { _Pragma("unroll") for (int _i = 0; _i < 2; ++_i) \
;         __builtin_amdgcn_global_load_lds((const unsigned*)((const char*)(gbase) + (voff)[_i]), (LAS unsigned*)(lds + (bufoff) + ldsw + _i * 8192), 16, 0, 0); } while (0)
; #define PG8_LDA(dst, b, h) do { _Pragma("unroll") for (int m = 0; m < 4; ++m) _Pragma("unroll") for (int k = 0; k < 2; ++k) dst[m][k] = *(const LAS bf16x8*)(lds + PG8_SA(b, h) + aoff + m * 2048 + k * 1024); } while (0)
; #define PG8_LDB(dst, b, h) do { _Pragma("unroll") for (int n = 0; n < 2; ++n) _Pragma("unroll") for (int k = 0; k < 2; ++k) dst[n][k] = *(const LAS bf16x8*)(lds + PG8_SB(b, h) + boff + n * 2048 + k * 1024); } while (0)
; #define PG8_MMA(ai, bj, At, Bt) do { __builtin_amdgcn_s_setprio(1); _Pragma("unroll") for (int m = 0; m < 4; ++m) _Pragma("unroll") for (int n = 0; n < 2; ++n) _Pragma("unroll") for (int k = 0; k < 2; ++k) \
;         acc[ai][bj][m][n] = __builtin_amdgcn_mfma_f32_16x16x32_bf16(Bt[n][k], At[m][k], acc[ai][bj][m][n], 0, 0, 0); __builtin_amdgcn_s_setprio(0); } while (0)
; #define PG8_WAIT_V(n) asm volatile("s_waitcnt vmcnt(" #n ")" ::: "memory")
; #define PG8_WAIT_L(n) asm volatile("s_waitcnt lgkmcnt(" #n ")" ::: "memory")
; #define PG8_BAR __builtin_amdgcn_s_barrier()
; #define PG8_SCHED __builtin_amdgcn_sched_barrier(0)
; template <class Epi, class Sched, bool ALIGN_EPI = false, bool SP2 = true>
; DI void gemm_phase(LAS unsigned char* lds, const Gemm g, const Sched& S, const Epi& E, f32x4 (&acc)[2][2][4][2]) {
;     ...
;             PG8_WAIT_V(8); PG8_WAIT_L(0); PG8_BAR; PG8_MMA(1, 0, At, B0); PG8_MMA(1, 1, At, B1); PG8_BAR; PG8_SCHED;
;             PG8_LDB(B0, 1, 0); PG8_LDB(B1, 1, 1); PG8_SCHED; PG8_LDA(At, 1, 0); PG8_STAGE(PG8_SA(0, 1), a2 + hstep, voffA);
;             PG8_WAIT_V(8); PG8_WAIT_L(0); PG8_BAR; PG8_MMA(0, 0, At, B0); PG8_MMA(0, 1, At, B1); PG8_BAR; PG8_SCHED;
	s_setprio 1
	s_waitcnt lgkmcnt(0)
	v_mfma_f32_16x16x32_bf16 v[76:79], v[144:147], v[180:183], v[76:79]
	v_mfma_f32_16x16x32_bf16 v[36:39], v[152:155], v[180:183], v[36:39]
	v_mfma_f32_16x16x32_bf16 v[68:71], v[144:147], v[188:191], v[68:71]
	v_mfma_f32_16x16x32_bf16 v[28:31], v[152:155], v[188:191], v[28:31]
	v_mfma_f32_16x16x32_bf16 v[72:75], v[144:147], v[196:199], v[72:75]
	v_mfma_f32_16x16x32_bf16 v[32:35], v[152:155], v[196:199], v[32:35]
	v_mfma_f32_16x16x32_bf16 v[64:67], v[144:147], v[206:209], v[64:67]
	v_mfma_f32_16x16x32_bf16 v[24:27], v[152:155], v[206:209], v[24:27]
	v_mfma_f32_16x16x32_bf16 v[76:79], v[148:151], v[184:187], v[76:79]
	v_mfma_f32_16x16x32_bf16 v[36:39], v[156:159], v[184:187], v[36:39]
	v_mfma_f32_16x16x32_bf16 v[68:71], v[148:151], v[192:195], v[68:71]
	v_mfma_f32_16x16x32_bf16 v[28:31], v[156:159], v[192:195], v[28:31]
	v_mfma_f32_16x16x32_bf16 v[72:75], v[148:151], v[202:205], v[72:75]
	v_mfma_f32_16x16x32_bf16 v[32:35], v[156:159], v[202:205], v[32:35]
	v_mfma_f32_16x16x32_bf16 v[64:67], v[148:151], v[210:213], v[64:67]
	v_mfma_f32_16x16x32_bf16 v[24:27], v[156:159], v[210:213], v[24:27]
	s_setprio 0
	s_setprio 1
	v_mfma_f32_16x16x32_bf16 v[16:19], v[160:163], v[180:183], v[16:19]
	v_mfma_f32_16x16x32_bf16 v[8:11], v[168:171], v[180:183], v[8:11]
	v_mfma_f32_16x16x32_bf16 v[12:15], v[160:163], v[188:191], v[12:15]
	v_mfma_f32_16x16x32_bf16 v[0:3], v[168:171], v[188:191], v[0:3]
	v_mfma_f32_16x16x32_bf16 v[4:7], v[160:163], v[196:199], v[4:7]
	v_mfma_f32_16x16x32_bf16 v[108:111], v[168:171], v[196:199], v[108:111]
	v_mfma_f32_16x16x32_bf16 v[120:123], v[160:163], v[206:209], v[120:123]
	v_mfma_f32_16x16x32_bf16 v[116:119], v[168:171], v[206:209], v[116:119]
	v_mfma_f32_16x16x32_bf16 v[16:19], v[164:167], v[184:187], v[16:19]
	v_mfma_f32_16x16x32_bf16 v[8:11], v[172:175], v[184:187], v[8:11]
	v_mfma_f32_16x16x32_bf16 v[12:15], v[164:167], v[192:195], v[12:15]
	v_mfma_f32_16x16x32_bf16 v[0:3], v[172:175], v[192:195], v[0:3]
	v_mfma_f32_16x16x32_bf16 v[4:7], v[164:167], v[202:205], v[4:7]
	v_mfma_f32_16x16x32_bf16 v[108:111], v[172:175], v[202:205], v[108:111]
	v_mfma_f32_16x16x32_bf16 v[120:123], v[164:167], v[210:213], v[120:123]
	v_mfma_f32_16x16x32_bf16 v[116:119], v[172:175], v[210:213], v[116:119]
	s_setprio 0
	s_barrier
	v_add_u32_e32 v156, s43, v142
	v_add_u32_e32 v172, s44, v142
	ds_read_b128 v[144:147], v156
	ds_read_b128 v[148:151], v156 offset:1024
	ds_read_b128 v[152:155], v156 offset:2048
	ds_read_b128 v[156:159], v156 offset:3072
	ds_read_b128 v[160:163], v172
	ds_read_b128 v[164:167], v172 offset:1024
	ds_read_b128 v[168:171], v172 offset:2048
	ds_read_b128 v[172:175], v172 offset:3072
	s_add_u32 s20, s20, 0x40000
	s_addc_u32 s21, s21, 0
	s_mov_b32 m0, s28
	v_lshl_add_u64 v[220:221], s[20:21], 0, v[130:131]
	ds_read_b128 v[180:183], v143 offset:32768
	ds_read_b128 v[184:187], v143 offset:33792
	ds_read_b128 v[188:191], v143 offset:34816
	ds_read_b128 v[192:195], v143 offset:35840
	ds_read_b128 v[196:199], v143 offset:36864
	ds_read_b128 v[202:205], v143 offset:37888
	ds_read_b128 v[206:209], v143 offset:38912
	ds_read_b128 v[210:213], v143 offset:39936
	v_lshl_add_u64 v[220:221], s[20:21], 0, v[128:129]
	s_mov_b32 m0, s29
	s_nop 0
	s_waitcnt vmcnt(0)
	s_waitcnt lgkmcnt(0)
	s_barrier
	s_setprio 1
	s_waitcnt lgkmcnt(0)
	v_mfma_f32_16x16x32_bf16 v[124:127], v[144:147], v[180:183], v[124:127]
	v_mfma_f32_16x16x32_bf16 v[112:115], v[152:155], v[180:183], v[112:115]
	v_mfma_f32_16x16x32_bf16 v[104:107], v[144:147], v[188:191], v[104:107]
	v_mfma_f32_16x16x32_bf16 v[96:99], v[152:155], v[188:191], v[96:99]
	v_mfma_f32_16x16x32_bf16 v[100:103], v[144:147], v[196:199], v[100:103]
	v_mfma_f32_16x16x32_bf16 v[88:91], v[152:155], v[196:199], v[88:91]
	v_mfma_f32_16x16x32_bf16 v[92:95], v[144:147], v[206:209], v[92:95]
	v_mfma_f32_16x16x32_bf16 v[84:87], v[152:155], v[206:209], v[84:87]
	v_mfma_f32_16x16x32_bf16 v[124:127], v[148:151], v[184:187], v[124:127]
	v_mfma_f32_16x16x32_bf16 v[112:115], v[156:159], v[184:187], v[112:115]
	v_mfma_f32_16x16x32_bf16 v[104:107], v[148:151], v[192:195], v[104:107]
	v_mfma_f32_16x16x32_bf16 v[96:99], v[156:159], v[192:195], v[96:99]
	v_mfma_f32_16x16x32_bf16 v[100:103], v[148:151], v[202:205], v[100:103]
	v_mfma_f32_16x16x32_bf16 v[88:91], v[156:159], v[202:205], v[88:91]
	v_mfma_f32_16x16x32_bf16 v[92:95], v[148:151], v[210:213], v[92:95]
	v_mfma_f32_16x16x32_bf16 v[84:87], v[156:159], v[210:213], v[84:87]
	s_setprio 0
	s_setprio 1
	v_mfma_f32_16x16x32_bf16 v[80:83], v[160:163], v[180:183], v[80:83]
	v_mfma_f32_16x16x32_bf16 v[60:63], v[168:171], v[180:183], v[60:63]
	v_mfma_f32_16x16x32_bf16 v[56:59], v[160:163], v[188:191], v[56:59]
	v_mfma_f32_16x16x32_bf16 v[48:51], v[168:171], v[188:191], v[48:51]
	v_mfma_f32_16x16x32_bf16 v[52:55], v[160:163], v[196:199], v[52:55]
	v_mfma_f32_16x16x32_bf16 v[40:43], v[168:171], v[196:199], v[40:43]
	v_mfma_f32_16x16x32_bf16 v[44:47], v[160:163], v[206:209], v[44:47]
	v_mfma_f32_16x16x32_bf16 v[20:23], v[168:171], v[206:209], v[20:23]
	v_mfma_f32_16x16x32_bf16 v[80:83], v[164:167], v[184:187], v[80:83]
	v_mfma_f32_16x16x32_bf16 v[60:63], v[172:175], v[184:187], v[60:63]
	v_mfma_f32_16x16x32_bf16 v[56:59], v[164:167], v[192:195], v[56:59]
	v_mfma_f32_16x16x32_bf16 v[48:51], v[172:175], v[192:195], v[48:51]
	v_mfma_f32_16x16x32_bf16 v[52:55], v[164:167], v[202:205], v[52:55]
	v_mfma_f32_16x16x32_bf16 v[40:43], v[172:175], v[202:205], v[40:43]
	v_mfma_f32_16x16x32_bf16 v[44:47], v[164:167], v[210:213], v[44:47]
	v_mfma_f32_16x16x32_bf16 v[20:23], v[172:175], v[210:213], v[20:23]
	s_setprio 0
	s_barrier
; #define PG8_STAGE(bufoff, gbase, voff) do { _Pragma("unroll") for (int _i = 0; _i < 2; ++_i) \
;         __builtin_amdgcn_global_load_lds((const unsigned*)((const char*)(gbase) + (voff)[_i]), (LAS unsigned*)(lds + (bufoff) + ldsw + _i * 8192), 16, 0, 0); } while (0)
; #define PG8_LDA(dst, b, h) do { _Pragma("unroll") for (int m = 0; m < 4; ++m) _Pragma("unroll") for (int k = 0; k < 2; ++k) dst[m][k] = *(const LAS bf16x8*)(lds + PG8_SA(b, h) + aoff + m * 2048 + k * 1024); } while (0)
; #define PG8_MMA(ai, bj, At, Bt) do { __builtin_amdgcn_s_setprio(1); _Pragma("unroll") for (int m = 0; m < 4; ++m) _Pragma("unroll") for (int n = 0; n < 2; ++n) _Pragma("unroll") for (int k = 0; k < 2; ++k) \
;         acc[ai][bj][m][n] = __builtin_amdgcn_mfma_f32_16x16x32_bf16(Bt[n][k], At[m][k], acc[ai][bj][m][n], 0, 0, 0); __builtin_amdgcn_s_setprio(0); } while (0)
; #define PG8_WAIT_V(n) asm volatile("s_waitcnt vmcnt(" #n ")" ::: "memory")
; #define PG8_WAIT_L(n) asm volatile("s_waitcnt lgkmcnt(" #n ")" ::: "memory")
; #define PG8_BAR __builtin_amdgcn_s_barrier()
; #define PG8_SCHED __builtin_amdgcn_sched_barrier(0)
; template <class Epi, class Sched, bool ALIGN_EPI = false, bool SP2 = true>
; DI void gemm_phase(LAS unsigned char* lds, const Gemm g, const Sched& S, const Epi& E, f32x4 (&acc)[2][2][4][2]) {
;     ...
;             PG8_LDA(At, 1, 1); PG8_STAGE(PG8_SB(1, 0), b3, voffB); PG8_STAGE(PG8_SB(1, 1), b3 + hstep, voffB); PG8_STAGE(PG8_SA(1, 0), a3, voffA);
;             PG8_WAIT_V(8); PG8_WAIT_L(0); PG8_BAR; PG8_MMA(1, 0, At, B0); PG8_MMA(1, 1, At, B1); PG8_BAR; PG8_SCHED;
	s_mov_b32 m0, s45
	v_lshl_add_u64 v[176:177], v[176:177], 0, s[6:7]
	s_add_u32 s18, s18, 0x40080
	ds_read_b128 v[180:183], v143 offset:49152
	ds_read_b128 v[184:187], v143 offset:50176
	ds_read_b128 v[188:191], v143 offset:51200
	ds_read_b128 v[192:195], v143 offset:52224
	ds_read_b128 v[196:199], v143 offset:53248
	ds_read_b128 v[202:205], v143 offset:54272
	ds_read_b128 v[206:209], v143 offset:55296
	ds_read_b128 v[210:213], v143 offset:56320
	v_lshl_add_u64 v[176:177], v[214:215], 0, s[6:7]
	s_mov_b32 m0, s46
	s_addc_u32 s19, s19, 0
	v_lshl_add_u64 v[176:177], s[18:19], 0, v[130:131]
	s_mov_b32 m0, s47
	s_nop 0
	v_lshl_add_u64 v[176:177], s[18:19], 0, v[128:129]
	s_mov_b32 m0, s48
	s_nop 0
	v_lshl_add_u64 v[176:177], v[216:217], 0, s[6:7]
	s_mov_b32 m0, s31
	s_nop 0
	v_lshl_add_u64 v[176:177], v[218:219], 0, s[6:7]
	s_mov_b32 m0, s34
	s_nop 0
	s_waitcnt vmcnt(0)
	s_waitcnt lgkmcnt(0)
	s_barrier
	s_setprio 1
	s_waitcnt lgkmcnt(0)
	v_mfma_f32_16x16x32_bf16 v[76:79], v[144:147], v[180:183], v[76:79]
	v_mfma_f32_16x16x32_bf16 v[36:39], v[152:155], v[180:183], v[36:39]
	v_mfma_f32_16x16x32_bf16 v[68:71], v[144:147], v[188:191], v[68:71]
	v_mfma_f32_16x16x32_bf16 v[28:31], v[152:155], v[188:191], v[28:31]
	v_mfma_f32_16x16x32_bf16 v[72:75], v[144:147], v[196:199], v[72:75]
	v_mfma_f32_16x16x32_bf16 v[32:35], v[152:155], v[196:199], v[32:35]
	v_mfma_f32_16x16x32_bf16 v[64:67], v[144:147], v[206:209], v[64:67]
	v_mfma_f32_16x16x32_bf16 v[24:27], v[152:155], v[206:209], v[24:27]
	v_mfma_f32_16x16x32_bf16 v[76:79], v[148:151], v[184:187], v[76:79]
	v_mfma_f32_16x16x32_bf16 v[36:39], v[156:159], v[184:187], v[36:39]
	v_mfma_f32_16x16x32_bf16 v[68:71], v[148:151], v[192:195], v[68:71]
	v_mfma_f32_16x16x32_bf16 v[28:31], v[156:159], v[192:195], v[28:31]
	v_mfma_f32_16x16x32_bf16 v[72:75], v[148:151], v[202:205], v[72:75]
	v_mfma_f32_16x16x32_bf16 v[32:35], v[156:159], v[202:205], v[32:35]
	v_mfma_f32_16x16x32_bf16 v[64:67], v[148:151], v[210:213], v[64:67]
	v_mfma_f32_16x16x32_bf16 v[24:27], v[156:159], v[210:213], v[24:27]
	s_setprio 0
	s_setprio 1
	v_mfma_f32_16x16x32_bf16 v[16:19], v[160:163], v[180:183], v[16:19]
	v_mfma_f32_16x16x32_bf16 v[8:11], v[168:171], v[180:183], v[8:11]
	v_mfma_f32_16x16x32_bf16 v[12:15], v[160:163], v[188:191], v[12:15]
	v_mfma_f32_16x16x32_bf16 v[0:3], v[168:171], v[188:191], v[0:3]
	v_mfma_f32_16x16x32_bf16 v[4:7], v[160:163], v[196:199], v[4:7]
	v_mfma_f32_16x16x32_bf16 v[108:111], v[168:171], v[196:199], v[108:111]
	v_mfma_f32_16x16x32_bf16 v[120:123], v[160:163], v[206:209], v[120:123]
	v_mfma_f32_16x16x32_bf16 v[116:119], v[168:171], v[206:209], v[116:119]
	v_mfma_f32_16x16x32_bf16 v[16:19], v[164:167], v[184:187], v[16:19]
	v_mfma_f32_16x16x32_bf16 v[8:11], v[172:175], v[184:187], v[8:11]
	v_mfma_f32_16x16x32_bf16 v[12:15], v[164:167], v[192:195], v[12:15]
	v_mfma_f32_16x16x32_bf16 v[0:3], v[172:175], v[192:195], v[0:3]
	v_mfma_f32_16x16x32_bf16 v[4:7], v[164:167], v[202:205], v[4:7]
	v_mfma_f32_16x16x32_bf16 v[108:111], v[172:175], v[202:205], v[108:111]
	v_mfma_f32_16x16x32_bf16 v[120:123], v[164:167], v[210:213], v[120:123]
	v_mfma_f32_16x16x32_bf16 v[116:119], v[172:175], v[210:213], v[116:119]
	s_setprio 0
	s_barrier
	s_add_i32 s59, s59, 2
	s_add_u32 s16, s16, 0x100
	s_addc_u32 s17, s17, 0
	s_cmp_gt_u32 s59, 13
	s_branch .Lafter_g2

; #define PG8_STAGE(bufoff, gbase, voff) do { _Pragma("unroll") for (int _i = 0; _i < 2; ++_i) \
;         __builtin_amdgcn_global_load_lds((const unsigned*)((const char*)(gbase) + (voff)[_i]), (LAS unsigned*)(lds + (bufoff) + ldsw + _i * 8192), 16, 0, 0); } while (0)
; #define PG8_LDA(dst, b, h) do { _Pragma("unroll") for (int m = 0; m < 4; ++m) _Pragma("unroll") for (int k = 0; k < 2; ++k) dst[m][k] = *(const LAS bf16x8*)(lds + PG8_SA(b, h) + aoff + m * 2048 + k * 1024); } while (0)
; #define PG8_LDB(dst, b, h) do { _Pragma("unroll") for (int n = 0; n < 2; ++n) _Pragma("unroll") for (int k = 0; k < 2; ++k) dst[n][k] = *(const LAS bf16x8*)(lds + PG8_SB(b, h) + boff + n * 2048 + k * 1024); } while (0)
; #define PG8_MMA(ai, bj, At, Bt) do { __builtin_amdgcn_s_setprio(1); _Pragma("unroll") for (int m = 0; m < 4; ++m) _Pragma("unroll") for (int n = 0; n < 2; ++n) _Pragma("unroll") for (int k = 0; k < 2; ++k) \
;         acc[ai][bj][m][n] = __builtin_amdgcn_mfma_f32_16x16x32_bf16(Bt[n][k], At[m][k], acc[ai][bj][m][n], 0, 0, 0); __builtin_amdgcn_s_setprio(0); } while (0)
; #define PG8_WAIT_V(n) asm volatile("s_waitcnt vmcnt(" #n ")" ::: "memory")
; #define PG8_WAIT_L(n) asm volatile("s_waitcnt lgkmcnt(" #n ")" ::: "memory")
; #define PG8_BAR __builtin_amdgcn_s_barrier()
; #define PG8_SCHED __builtin_amdgcn_sched_barrier(0)
; template <class Epi, class Sched, bool ALIGN_EPI = false, bool SP2 = true>
; DI void gemm_phase(LAS unsigned char* lds, const Gemm g, const Sched& S, const Epi& E, f32x4 (&acc)[2][2][4][2]) {
;     ...
;             PG8_LDB(B0, 0, 0); PG8_LDB(B1, 0, 1); PG8_SCHED; PG8_LDA(At, 0, 0); PG8_STAGE(PG8_SA(1, 1), a1 + hstep, voffA);
;             PG8_WAIT_V(8); PG8_WAIT_L(0); PG8_BAR; PG8_MMA(0, 0, At, B0); PG8_MMA(0, 1, At, B1); PG8_BAR; PG8_SCHED;
;             PG8_LDA(At, 0, 1); PG8_STAGE(PG8_SB(0, 0), b2, voffB); PG8_STAGE(PG8_SB(0, 1), b2 + hstep, voffB); PG8_STAGE(PG8_SA(0, 0), a2, voffA);
;             PG8_WAIT_V(8); PG8_WAIT_L(0); PG8_BAR; PG8_MMA(1, 0, At, B0); PG8_MMA(1, 1, At, B1); PG8_BAR; PG8_SCHED;
.LBB0_541:
	s_cmp_eq_u32 s59, 12
	s_cbranch_scc1 .Lpeel_g2
	v_add_u32_e32 v156, s35, v142
	v_add_u32_e32 v172, s36, v142
	s_add_u32 s18, s0, s16
	ds_read_b128 v[144:147], v156
	ds_read_b128 v[148:151], v156 offset:1024
	ds_read_b128 v[152:155], v156 offset:2048
	ds_read_b128 v[156:159], v156 offset:3072
	ds_read_b128 v[160:163], v172
	ds_read_b128 v[164:167], v172 offset:1024
	ds_read_b128 v[168:171], v172 offset:2048
	ds_read_b128 v[172:175], v172 offset:3072
	s_addc_u32 s19, s1, s17
	s_add_u32 s18, s18, 0x100
	s_addc_u32 s19, s19, 0
	s_add_u32 s60, s52, s16
	s_addc_u32 s61, s53, s17
	s_cmpk_eq_i32 s16, 0x700
	s_cselect_b32 s21, s55, s19
	s_cselect_b32 s20, s56, s18
	s_cselect_b32 s19, s57, s61
	s_cselect_b32 s18, s58, s60
	s_mov_b32 m0, s37
	v_lshl_add_u64 v[176:177], v[136:137], 0, s[16:17]
	ds_read_b128 v[180:183], v143
	ds_read_b128 v[184:187], v143 offset:1024
	ds_read_b128 v[188:191], v143 offset:2048
	ds_read_b128 v[192:195], v143 offset:3072
	ds_read_b128 v[196:199], v143 offset:4096
	ds_read_b128 v[202:205], v143 offset:5120
	ds_read_b128 v[206:209], v143 offset:6144
	ds_read_b128 v[210:213], v143 offset:7168
	global_load_lds_dwordx4 v[176:177], off
	v_lshl_add_u64 v[176:177], v[138:139], 0, s[16:17]
	s_mov_b32 m0, s38
	s_nop 0
	global_load_lds_dwordx4 v[176:177], off
	s_waitcnt vmcnt(8)
	s_waitcnt lgkmcnt(0)
	s_barrier
	s_setprio 1
	s_waitcnt lgkmcnt(0)
	v_mfma_f32_16x16x32_bf16 v[124:127], v[144:147], v[180:183], v[124:127]
	v_mfma_f32_16x16x32_bf16 v[112:115], v[152:155], v[180:183], v[112:115]
	v_mfma_f32_16x16x32_bf16 v[104:107], v[144:147], v[188:191], v[104:107]
	v_mfma_f32_16x16x32_bf16 v[96:99], v[152:155], v[188:191], v[96:99]
	v_mfma_f32_16x16x32_bf16 v[100:103], v[144:147], v[196:199], v[100:103]
	v_mfma_f32_16x16x32_bf16 v[88:91], v[152:155], v[196:199], v[88:91]
	v_mfma_f32_16x16x32_bf16 v[92:95], v[144:147], v[206:209], v[92:95]
	v_mfma_f32_16x16x32_bf16 v[84:87], v[152:155], v[206:209], v[84:87]
	v_mfma_f32_16x16x32_bf16 v[124:127], v[148:151], v[184:187], v[124:127]
	v_mfma_f32_16x16x32_bf16 v[112:115], v[156:159], v[184:187], v[112:115]
	v_mfma_f32_16x16x32_bf16 v[104:107], v[148:151], v[192:195], v[104:107]
	v_mfma_f32_16x16x32_bf16 v[96:99], v[156:159], v[192:195], v[96:99]
	v_mfma_f32_16x16x32_bf16 v[100:103], v[148:151], v[202:205], v[100:103]
	v_mfma_f32_16x16x32_bf16 v[88:91], v[156:159], v[202:205], v[88:91]
	v_mfma_f32_16x16x32_bf16 v[92:95], v[148:151], v[210:213], v[92:95]
	v_mfma_f32_16x16x32_bf16 v[84:87], v[156:159], v[210:213], v[84:87]
	s_setprio 0
	s_setprio 1
	v_mfma_f32_16x16x32_bf16 v[80:83], v[160:163], v[180:183], v[80:83]
	v_mfma_f32_16x16x32_bf16 v[60:63], v[168:171], v[180:183], v[60:63]
	v_mfma_f32_16x16x32_bf16 v[56:59], v[160:163], v[188:191], v[56:59]
	v_mfma_f32_16x16x32_bf16 v[48:51], v[168:171], v[188:191], v[48:51]
	v_mfma_f32_16x16x32_bf16 v[52:55], v[160:163], v[196:199], v[52:55]
	v_mfma_f32_16x16x32_bf16 v[40:43], v[168:171], v[196:199], v[40:43]
	v_mfma_f32_16x16x32_bf16 v[44:47], v[160:163], v[206:209], v[44:47]
	v_mfma_f32_16x16x32_bf16 v[20:23], v[168:171], v[206:209], v[20:23]
	v_mfma_f32_16x16x32_bf16 v[80:83], v[164:167], v[184:187], v[80:83]
	v_mfma_f32_16x16x32_bf16 v[60:63], v[172:175], v[184:187], v[60:63]
	v_mfma_f32_16x16x32_bf16 v[56:59], v[164:167], v[192:195], v[56:59]
	v_mfma_f32_16x16x32_bf16 v[48:51], v[172:175], v[192:195], v[48:51]
	v_mfma_f32_16x16x32_bf16 v[52:55], v[164:167], v[202:205], v[52:55]
	v_mfma_f32_16x16x32_bf16 v[40:43], v[172:175], v[202:205], v[40:43]
	v_mfma_f32_16x16x32_bf16 v[44:47], v[164:167], v[210:213], v[44:47]
	v_mfma_f32_16x16x32_bf16 v[20:23], v[172:175], v[210:213], v[20:23]
	s_setprio 0
	s_barrier
	s_mov_b32 m0, s39
	v_lshl_add_u64 v[176:177], s[18:19], 0, v[130:131]
	s_add_u32 s60, s18, 0x40000
	ds_read_b128 v[180:183], v143 offset:16384
	ds_read_b128 v[184:187], v143 offset:17408
	ds_read_b128 v[188:191], v143 offset:18432
	ds_read_b128 v[192:195], v143 offset:19456
	ds_read_b128 v[196:199], v143 offset:20480
	ds_read_b128 v[202:205], v143 offset:21504
	ds_read_b128 v[206:209], v143 offset:22528
	ds_read_b128 v[210:213], v143 offset:23552
	global_load_lds_dwordx4 v[176:177], off
	v_lshl_add_u64 v[214:215], s[18:19], 0, v[128:129]
	s_mov_b32 m0, s40
	s_addc_u32 s61, s19, 0
	global_load_lds_dwordx4 v[214:215], off
	v_lshl_add_u64 v[216:217], s[60:61], 0, v[130:131]
	s_mov_b32 m0, s41
	v_lshl_add_u64 v[218:219], s[20:21], 0, v[128:129]
	global_load_lds_dwordx4 v[216:217], off
	v_lshl_add_u64 v[216:217], s[60:61], 0, v[128:129]
	s_mov_b32 m0, s42
	s_nop 0
	global_load_lds_dwordx4 v[216:217], off
	v_lshl_add_u64 v[216:217], s[20:21], 0, v[130:131]
	s_mov_b32 m0, s5
	s_nop 0
	global_load_lds_dwordx4 v[216:217], off
	s_mov_b32 m0, s27
	s_nop 0
	global_load_lds_dwordx4 v[218:219], off
	s_waitcnt vmcnt(8)
	s_waitcnt lgkmcnt(0)
	s_barrier
; #define PG8_STAGE(bufoff, gbase, voff) do { _Pragma("unroll") for (int _i = 0; _i < 2; ++_i) \
;         __builtin_amdgcn_global_load_lds((const unsigned*)((const char*)(gbase) + (voff)[_i]), (LAS unsigned*)(lds + (bufoff) + ldsw + _i * 8192), 16, 0, 0); } while (0)
; #define PG8_LDA(dst, b, h) do { _Pragma("unroll") for (int m = 0; m < 4; ++m) _Pragma("unroll") for (int k = 0; k < 2; ++k) dst[m][k] = *(const LAS bf16x8*)(lds + PG8_SA(b, h) + aoff + m * 2048 + k * 1024); } while (0)
; #define PG8_LDB(dst, b, h) do { _Pragma("unroll") for (int n = 0; n < 2; ++n) _Pragma("unroll") for (int k = 0; k < 2; ++k) dst[n][k] = *(const LAS bf16x8*)(lds + PG8_SB(b, h) + boff + n * 2048 + k * 1024); } while (0)
; #define PG8_MMA(ai, bj, At, Bt) do { __builtin_amdgcn_s_setprio(1); _Pragma("unroll") for (int m = 0; m < 4; ++m) _Pragma("unroll") for (int n = 0; n < 2; ++n) _Pragma("unroll") for (int k = 0; k < 2; ++k) \
;         acc[ai][bj][m][n] = __builtin_amdgcn_mfma_f32_16x16x32_bf16(Bt[n][k], At[m][k], acc[ai][bj][m][n], 0, 0, 0); __builtin_amdgcn_s_setprio(0); } while (0)
; #define PG8_WAIT_V(n) asm volatile("s_waitcnt vmcnt(" #n ")" ::: "memory")
; #define PG8_WAIT_L(n) asm volatile("s_waitcnt lgkmcnt(" #n ")" ::: "memory")
; #define PG8_BAR __builtin_amdgcn_s_barrier()
; #define PG8_SCHED __builtin_amdgcn_sched_barrier(0)
; template <class Epi, class Sched, bool ALIGN_EPI = false, bool SP2 = true>
; DI void gemm_phase(LAS unsigned char* lds, const Gemm g, const Sched& S, const Epi& E, f32x4 (&acc)[2][2][4][2]) {
;     ...
;             PG8_WAIT_V(8); PG8_WAIT_L(0); PG8_BAR; PG8_MMA(1, 0, At, B0); PG8_MMA(1, 1, At, B1); PG8_BAR; PG8_SCHED;
;             PG8_LDB(B0, 1, 0); PG8_LDB(B1, 1, 1); PG8_SCHED; PG8_LDA(At, 1, 0); PG8_STAGE(PG8_SA(0, 1), a2 + hstep, voffA);
;             PG8_WAIT_V(8); PG8_WAIT_L(0); PG8_BAR; PG8_MMA(0, 0, At, B0); PG8_MMA(0, 1, At, B1); PG8_BAR; PG8_SCHED;
	s_setprio 1
	s_waitcnt lgkmcnt(0)
	v_mfma_f32_16x16x32_bf16 v[76:79], v[144:147], v[180:183], v[76:79]
	v_mfma_f32_16x16x32_bf16 v[36:39], v[152:155], v[180:183], v[36:39]
	v_mfma_f32_16x16x32_bf16 v[68:71], v[144:147], v[188:191], v[68:71]
	v_mfma_f32_16x16x32_bf16 v[28:31], v[152:155], v[188:191], v[28:31]
	v_mfma_f32_16x16x32_bf16 v[72:75], v[144:147], v[196:199], v[72:75]
	v_mfma_f32_16x16x32_bf16 v[32:35], v[152:155], v[196:199], v[32:35]
	v_mfma_f32_16x16x32_bf16 v[64:67], v[144:147], v[206:209], v[64:67]
	v_mfma_f32_16x16x32_bf16 v[24:27], v[152:155], v[206:209], v[24:27]
	v_mfma_f32_16x16x32_bf16 v[76:79], v[148:151], v[184:187], v[76:79]
	v_mfma_f32_16x16x32_bf16 v[36:39], v[156:159], v[184:187], v[36:39]
	v_mfma_f32_16x16x32_bf16 v[68:71], v[148:151], v[192:195], v[68:71]
	v_mfma_f32_16x16x32_bf16 v[28:31], v[156:159], v[192:195], v[28:31]
	v_mfma_f32_16x16x32_bf16 v[72:75], v[148:151], v[202:205], v[72:75]
	v_mfma_f32_16x16x32_bf16 v[32:35], v[156:159], v[202:205], v[32:35]
	v_mfma_f32_16x16x32_bf16 v[64:67], v[148:151], v[210:213], v[64:67]
	v_mfma_f32_16x16x32_bf16 v[24:27], v[156:159], v[210:213], v[24:27]
	s_setprio 0
	s_setprio 1
	v_mfma_f32_16x16x32_bf16 v[16:19], v[160:163], v[180:183], v[16:19]
	v_mfma_f32_16x16x32_bf16 v[8:11], v[168:171], v[180:183], v[8:11]
	v_mfma_f32_16x16x32_bf16 v[12:15], v[160:163], v[188:191], v[12:15]
	v_mfma_f32_16x16x32_bf16 v[0:3], v[168:171], v[188:191], v[0:3]
	v_mfma_f32_16x16x32_bf16 v[4:7], v[160:163], v[196:199], v[4:7]
	v_mfma_f32_16x16x32_bf16 v[108:111], v[168:171], v[196:199], v[108:111]
	v_mfma_f32_16x16x32_bf16 v[120:123], v[160:163], v[206:209], v[120:123]
	v_mfma_f32_16x16x32_bf16 v[116:119], v[168:171], v[206:209], v[116:119]
	v_mfma_f32_16x16x32_bf16 v[16:19], v[164:167], v[184:187], v[16:19]
	v_mfma_f32_16x16x32_bf16 v[8:11], v[172:175], v[184:187], v[8:11]
	v_mfma_f32_16x16x32_bf16 v[12:15], v[164:167], v[192:195], v[12:15]
	v_mfma_f32_16x16x32_bf16 v[0:3], v[172:175], v[192:195], v[0:3]
	v_mfma_f32_16x16x32_bf16 v[4:7], v[164:167], v[202:205], v[4:7]
	v_mfma_f32_16x16x32_bf16 v[108:111], v[172:175], v[202:205], v[108:111]
	v_mfma_f32_16x16x32_bf16 v[120:123], v[164:167], v[210:213], v[120:123]
	v_mfma_f32_16x16x32_bf16 v[116:119], v[172:175], v[210:213], v[116:119]
	s_setprio 0
	s_barrier
	v_add_u32_e32 v156, s43, v142
	v_add_u32_e32 v172, s44, v142
	ds_read_b128 v[144:147], v156
	ds_read_b128 v[148:151], v156 offset:1024
	ds_read_b128 v[152:155], v156 offset:2048
	ds_read_b128 v[156:159], v156 offset:3072
	ds_read_b128 v[160:163], v172
	ds_read_b128 v[164:167], v172 offset:1024
	ds_read_b128 v[168:171], v172 offset:2048
	ds_read_b128 v[172:175], v172 offset:3072
	s_add_u32 s20, s20, 0x40000
	s_addc_u32 s21, s21, 0
	s_mov_b32 m0, s28
	v_lshl_add_u64 v[220:221], s[20:21], 0, v[130:131]
	ds_read_b128 v[180:183], v143 offset:32768
	ds_read_b128 v[184:187], v143 offset:33792
	ds_read_b128 v[188:191], v143 offset:34816
	ds_read_b128 v[192:195], v143 offset:35840
	ds_read_b128 v[196:199], v143 offset:36864
	ds_read_b128 v[202:205], v143 offset:37888
	ds_read_b128 v[206:209], v143 offset:38912
	ds_read_b128 v[210:213], v143 offset:39936
	global_load_lds_dwordx4 v[220:221], off
	v_lshl_add_u64 v[220:221], s[20:21], 0, v[128:129]
	s_mov_b32 m0, s29
	s_nop 0
	global_load_lds_dwordx4 v[220:221], off
	s_waitcnt vmcnt(8)
	s_waitcnt lgkmcnt(0)
	s_barrier
	s_setprio 1
	s_waitcnt lgkmcnt(0)
	v_mfma_f32_16x16x32_bf16 v[124:127], v[144:147], v[180:183], v[124:127]
	v_mfma_f32_16x16x32_bf16 v[112:115], v[152:155], v[180:183], v[112:115]
	v_mfma_f32_16x16x32_bf16 v[104:107], v[144:147], v[188:191], v[104:107]
	v_mfma_f32_16x16x32_bf16 v[96:99], v[152:155], v[188:191], v[96:99]
	v_mfma_f32_16x16x32_bf16 v[100:103], v[144:147], v[196:199], v[100:103]
	v_mfma_f32_16x16x32_bf16 v[88:91], v[152:155], v[196:199], v[88:91]
	v_mfma_f32_16x16x32_bf16 v[92:95], v[144:147], v[206:209], v[92:95]
	v_mfma_f32_16x16x32_bf16 v[84:87], v[152:155], v[206:209], v[84:87]
	v_mfma_f32_16x16x32_bf16 v[124:127], v[148:151], v[184:187], v[124:127]
	v_mfma_f32_16x16x32_bf16 v[112:115], v[156:159], v[184:187], v[112:115]
	v_mfma_f32_16x16x32_bf16 v[104:107], v[148:151], v[192:195], v[104:107]
	v_mfma_f32_16x16x32_bf16 v[96:99], v[156:159], v[192:195], v[96:99]
	v_mfma_f32_16x16x32_bf16 v[100:103], v[148:151], v[202:205], v[100:103]
	v_mfma_f32_16x16x32_bf16 v[88:91], v[156:159], v[202:205], v[88:91]
	v_mfma_f32_16x16x32_bf16 v[92:95], v[148:151], v[210:213], v[92:95]
	v_mfma_f32_16x16x32_bf16 v[84:87], v[156:159], v[210:213], v[84:87]
	s_setprio 0
	s_setprio 1
	v_mfma_f32_16x16x32_bf16 v[80:83], v[160:163], v[180:183], v[80:83]
	v_mfma_f32_16x16x32_bf16 v[60:63], v[168:171], v[180:183], v[60:63]
	v_mfma_f32_16x16x32_bf16 v[56:59], v[160:163], v[188:191], v[56:59]
	v_mfma_f32_16x16x32_bf16 v[48:51], v[168:171], v[188:191], v[48:51]
	v_mfma_f32_16x16x32_bf16 v[52:55], v[160:163], v[196:199], v[52:55]
	v_mfma_f32_16x16x32_bf16 v[40:43], v[168:171], v[196:199], v[40:43]
	v_mfma_f32_16x16x32_bf16 v[44:47], v[160:163], v[206:209], v[44:47]
	v_mfma_f32_16x16x32_bf16 v[20:23], v[168:171], v[206:209], v[20:23]
	v_mfma_f32_16x16x32_bf16 v[80:83], v[164:167], v[184:187], v[80:83]
	v_mfma_f32_16x16x32_bf16 v[60:63], v[172:175], v[184:187], v[60:63]
	v_mfma_f32_16x16x32_bf16 v[56:59], v[164:167], v[192:195], v[56:59]
	v_mfma_f32_16x16x32_bf16 v[48:51], v[172:175], v[192:195], v[48:51]
	v_mfma_f32_16x16x32_bf16 v[52:55], v[164:167], v[202:205], v[52:55]
	v_mfma_f32_16x16x32_bf16 v[40:43], v[172:175], v[202:205], v[40:43]
	v_mfma_f32_16x16x32_bf16 v[44:47], v[164:167], v[210:213], v[44:47]
	v_mfma_f32_16x16x32_bf16 v[20:23], v[172:175], v[210:213], v[20:23]
	s_setprio 0
	s_barrier
; #define PG8_STAGE(bufoff, gbase, voff) do { _Pragma("unroll") for (int _i = 0; _i < 2; ++_i) \
;         __builtin_amdgcn_global_load_lds((const unsigned*)((const char*)(gbase) + (voff)[_i]), (LAS unsigned*)(lds + (bufoff) + ldsw + _i * 8192), 16, 0, 0); } while (0)
; #define PG8_LDA(dst, b, h) do { _Pragma("unroll") for (int m = 0; m < 4; ++m) _Pragma("unroll") for (int k = 0; k < 2; ++k) dst[m][k] = *(const LAS bf16x8*)(lds + PG8_SA(b, h) + aoff + m * 2048 + k * 1024); } while (0)
; #define PG8_MMA(ai, bj, At, Bt) do { __builtin_amdgcn_s_setprio(1); _Pragma("unroll") for (int m = 0; m < 4; ++m) _Pragma("unroll") for (int n = 0; n < 2; ++n) _Pragma("unroll") for (int k = 0; k < 2; ++k) \
;         acc[ai][bj][m][n] = __builtin_amdgcn_mfma_f32_16x16x32_bf16(Bt[n][k], At[m][k], acc[ai][bj][m][n], 0, 0, 0); __builtin_amdgcn_s_setprio(0); } while (0)
; #define PG8_WAIT_V(n) asm volatile("s_waitcnt vmcnt(" #n ")" ::: "memory")
; #define PG8_WAIT_L(n) asm volatile("s_waitcnt lgkmcnt(" #n ")" ::: "memory")
; #define PG8_BAR __builtin_amdgcn_s_barrier()
; #define PG8_SCHED __builtin_amdgcn_sched_barrier(0)
; template <class Epi, class Sched, bool ALIGN_EPI = false, bool SP2 = true>
; DI void gemm_phase(LAS unsigned char* lds, const Gemm g, const Sched& S, const Epi& E, f32x4 (&acc)[2][2][4][2]) {
;     ...
;             PG8_LDA(At, 1, 1); PG8_STAGE(PG8_SB(1, 0), b3, voffB); PG8_STAGE(PG8_SB(1, 1), b3 + hstep, voffB); PG8_STAGE(PG8_SA(1, 0), a3, voffA);
;             PG8_WAIT_V(8); PG8_WAIT_L(0); PG8_BAR; PG8_MMA(1, 0, At, B0); PG8_MMA(1, 1, At, B1); PG8_BAR; PG8_SCHED;
;     ...
;         if (!has_next) break;
	s_mov_b32 m0, s45
	v_lshl_add_u64 v[176:177], v[176:177], 0, s[6:7]
	s_add_u32 s18, s18, 0x40080
	ds_read_b128 v[180:183], v143 offset:49152
	ds_read_b128 v[184:187], v143 offset:50176
	ds_read_b128 v[188:191], v143 offset:51200
	ds_read_b128 v[192:195], v143 offset:52224
	ds_read_b128 v[196:199], v143 offset:53248
	ds_read_b128 v[202:205], v143 offset:54272
	ds_read_b128 v[206:209], v143 offset:55296
	ds_read_b128 v[210:213], v143 offset:56320
	global_load_lds_dwordx4 v[176:177], off
	v_lshl_add_u64 v[176:177], v[214:215], 0, s[6:7]
	s_mov_b32 m0, s46
	s_addc_u32 s19, s19, 0
	global_load_lds_dwordx4 v[176:177], off
	v_lshl_add_u64 v[176:177], s[18:19], 0, v[130:131]
	s_mov_b32 m0, s47
	s_nop 0
	global_load_lds_dwordx4 v[176:177], off
	v_lshl_add_u64 v[176:177], s[18:19], 0, v[128:129]
	s_mov_b32 m0, s48
	s_nop 0
	global_load_lds_dwordx4 v[176:177], off
	v_lshl_add_u64 v[176:177], v[216:217], 0, s[6:7]
	s_mov_b32 m0, s31
	s_nop 0
	global_load_lds_dwordx4 v[176:177], off
	v_lshl_add_u64 v[176:177], v[218:219], 0, s[6:7]
	s_mov_b32 m0, s34
	s_nop 0
	global_load_lds_dwordx4 v[176:177], off
	s_waitcnt vmcnt(8)
	s_waitcnt lgkmcnt(0)
	s_barrier
	s_setprio 1
	s_waitcnt lgkmcnt(0)
	v_mfma_f32_16x16x32_bf16 v[76:79], v[144:147], v[180:183], v[76:79]
	v_mfma_f32_16x16x32_bf16 v[36:39], v[152:155], v[180:183], v[36:39]
	v_mfma_f32_16x16x32_bf16 v[68:71], v[144:147], v[188:191], v[68:71]
	v_mfma_f32_16x16x32_bf16 v[28:31], v[152:155], v[188:191], v[28:31]
	v_mfma_f32_16x16x32_bf16 v[72:75], v[144:147], v[196:199], v[72:75]
	v_mfma_f32_16x16x32_bf16 v[32:35], v[152:155], v[196:199], v[32:35]
	v_mfma_f32_16x16x32_bf16 v[64:67], v[144:147], v[206:209], v[64:67]
	v_mfma_f32_16x16x32_bf16 v[24:27], v[152:155], v[206:209], v[24:27]
	v_mfma_f32_16x16x32_bf16 v[76:79], v[148:151], v[184:187], v[76:79]
	v_mfma_f32_16x16x32_bf16 v[36:39], v[156:159], v[184:187], v[36:39]
	v_mfma_f32_16x16x32_bf16 v[68:71], v[148:151], v[192:195], v[68:71]
	v_mfma_f32_16x16x32_bf16 v[28:31], v[156:159], v[192:195], v[28:31]
	v_mfma_f32_16x16x32_bf16 v[72:75], v[148:151], v[202:205], v[72:75]
	v_mfma_f32_16x16x32_bf16 v[32:35], v[156:159], v[202:205], v[32:35]
	v_mfma_f32_16x16x32_bf16 v[64:67], v[148:151], v[210:213], v[64:67]
	v_mfma_f32_16x16x32_bf16 v[24:27], v[156:159], v[210:213], v[24:27]
	s_setprio 0
	s_setprio 1
	v_mfma_f32_16x16x32_bf16 v[16:19], v[160:163], v[180:183], v[16:19]
	v_mfma_f32_16x16x32_bf16 v[8:11], v[168:171], v[180:183], v[8:11]
	v_mfma_f32_16x16x32_bf16 v[12:15], v[160:163], v[188:191], v[12:15]
	v_mfma_f32_16x16x32_bf16 v[0:3], v[168:171], v[188:191], v[0:3]
	v_mfma_f32_16x16x32_bf16 v[4:7], v[160:163], v[196:199], v[4:7]
	v_mfma_f32_16x16x32_bf16 v[108:111], v[168:171], v[196:199], v[108:111]
	v_mfma_f32_16x16x32_bf16 v[120:123], v[160:163], v[206:209], v[120:123]
	v_mfma_f32_16x16x32_bf16 v[116:119], v[168:171], v[206:209], v[116:119]
	v_mfma_f32_16x16x32_bf16 v[16:19], v[164:167], v[184:187], v[16:19]
	v_mfma_f32_16x16x32_bf16 v[8:11], v[172:175], v[184:187], v[8:11]
	v_mfma_f32_16x16x32_bf16 v[12:15], v[164:167], v[192:195], v[12:15]
	v_mfma_f32_16x16x32_bf16 v[0:3], v[172:175], v[192:195], v[0:3]
	v_mfma_f32_16x16x32_bf16 v[4:7], v[164:167], v[202:205], v[4:7]
	v_mfma_f32_16x16x32_bf16 v[108:111], v[172:175], v[202:205], v[108:111]
	v_mfma_f32_16x16x32_bf16 v[120:123], v[164:167], v[210:213], v[120:123]
	v_mfma_f32_16x16x32_bf16 v[116:119], v[172:175], v[210:213], v[116:119]
	s_setprio 0
	s_barrier
	s_add_i32 s59, s59, 2
	s_add_u32 s16, s16, 0x100
	s_addc_u32 s17, s17, 0
	s_cmp_gt_u32 s59, 13
	s_cbranch_scc0 .LBB0_541
.Lafter_g2:
	s_add_u32 s16, s52, 0xffffff00
	s_addc_u32 s17, s53, -1
	s_andn2_b64 vcc, exec, s[12:13]
	s_cbranch_vccz .LBB0_539
	s_mov_b64 s[8:9], s[16:17]
	s_andn2_b64 vcc, exec, s[10:11]
	s_cbranch_vccnz .LBB0_540
